# GEMM K-loops: 14 LDS-DMA loads use the SGPR-base + VGPR-offset form instead of a 64-bit VALU address add
# baseline (speedup 1.0000x reference)
.LBB0_151:
	s_add_u32 s4, s0, 0xfffc0080
	s_addc_u32 s5, s1, -1
	s_add_i32 s18, 0, 0x10000
	s_cmp_eq_u32 s77, 12
	s_cselect_b32 s39, s79, s5
	s_cselect_b32 s38, s96, s4
	v_add_u32_e32 v0, s18, v161
	s_cselect_b32 s5, s51, vcc_hi
	s_cselect_b32 s4, s97, vcc_lo
	s_add_i32 s20, 0, 0x14000
	ds_read_b128 v[154:157], v0
	ds_read_b128 v[172:175], v0 offset:1024
	ds_read_b128 v[176:179], v0 offset:2048
	ds_read_b128 v[180:183], v0 offset:3072
	v_add_u32_e32 v0, s20, v161
	ds_read_b128 v[184:187], v0
	ds_read_b128 v[188:191], v0 offset:1024
	ds_read_b128 v[204:207], v0 offset:2048
	ds_read_b128 v[208:211], v0 offset:3072
	v_lshl_add_u64 v[158:159], s[0:1], 0, v[150:151]
	s_add_i32 m0, s31, 0xc000
	ds_read_b128 v[212:215], v170
	ds_read_b128 v[216:219], v170 offset:1024
	ds_read_b128 v[220:223], v170 offset:2048
	ds_read_b128 v[224:227], v170 offset:3072
	ds_read_b128 v[228:231], v170 offset:4096
	ds_read_b128 v[232:235], v170 offset:5120
	ds_read_b128 v[236:239], v170 offset:6144
	ds_read_b128 v[240:243], v170 offset:7168
	global_load_lds_dwordx4 v[158:159], off
	v_lshl_add_u64 v[158:159], s[0:1], 0, v[152:153]
	s_add_i32 m0, s31, 0xe000
	s_nop 0
	global_load_lds_dwordx4 v[158:159], off
	s_waitcnt vmcnt(8)
	s_waitcnt lgkmcnt(0)
	s_barrier
	s_setprio 1
	s_waitcnt lgkmcnt(0)
	v_mfma_f32_16x16x32_bf16 v[126:129], v[154:157], v[212:215], v[126:129]
	v_mfma_f32_16x16x32_bf16 v[122:125], v[176:179], v[212:215], v[122:125]
	v_mfma_f32_16x16x32_bf16 v[110:113], v[154:157], v[220:223], v[110:113]
	v_mfma_f32_16x16x32_bf16 v[106:109], v[176:179], v[220:223], v[106:109]
	v_mfma_f32_16x16x32_bf16 v[94:97], v[154:157], v[228:231], v[94:97]
	v_mfma_f32_16x16x32_bf16 v[90:93], v[176:179], v[228:231], v[90:93]
	v_mfma_f32_16x16x32_bf16 v[78:81], v[154:157], v[236:239], v[78:81]
	v_mfma_f32_16x16x32_bf16 v[74:77], v[176:179], v[236:239], v[74:77]
	v_mfma_f32_16x16x32_bf16 v[126:129], v[172:175], v[216:219], v[126:129]
	v_mfma_f32_16x16x32_bf16 v[122:125], v[180:183], v[216:219], v[122:125]
	v_mfma_f32_16x16x32_bf16 v[110:113], v[172:175], v[224:227], v[110:113]
	v_mfma_f32_16x16x32_bf16 v[106:109], v[180:183], v[224:227], v[106:109]
	v_mfma_f32_16x16x32_bf16 v[94:97], v[172:175], v[232:235], v[94:97]
	v_mfma_f32_16x16x32_bf16 v[90:93], v[180:183], v[232:235], v[90:93]
	v_mfma_f32_16x16x32_bf16 v[78:81], v[172:175], v[240:243], v[78:81]
	v_mfma_f32_16x16x32_bf16 v[74:77], v[180:183], v[240:243], v[74:77]
	s_setprio 0
	s_setprio 1
	v_mfma_f32_16x16x32_bf16 v[118:121], v[184:187], v[212:215], v[118:121]
	v_mfma_f32_16x16x32_bf16 v[114:117], v[204:207], v[212:215], v[114:117]
	v_mfma_f32_16x16x32_bf16 v[102:105], v[184:187], v[220:223], v[102:105]
	v_mfma_f32_16x16x32_bf16 v[98:101], v[204:207], v[220:223], v[98:101]
	v_mfma_f32_16x16x32_bf16 v[86:89], v[184:187], v[228:231], v[86:89]
	v_mfma_f32_16x16x32_bf16 v[82:85], v[204:207], v[228:231], v[82:85]
	v_mfma_f32_16x16x32_bf16 v[70:73], v[184:187], v[236:239], v[70:73]
	v_mfma_f32_16x16x32_bf16 v[66:69], v[204:207], v[236:239], v[66:69]
	v_mfma_f32_16x16x32_bf16 v[118:121], v[188:191], v[216:219], v[118:121]
	v_mfma_f32_16x16x32_bf16 v[114:117], v[208:211], v[216:219], v[114:117]
	v_mfma_f32_16x16x32_bf16 v[102:105], v[188:191], v[224:227], v[102:105]
	v_mfma_f32_16x16x32_bf16 v[98:101], v[208:211], v[224:227], v[98:101]
	v_mfma_f32_16x16x32_bf16 v[86:89], v[188:191], v[232:235], v[86:89]
	v_mfma_f32_16x16x32_bf16 v[82:85], v[208:211], v[232:235], v[82:85]
	v_mfma_f32_16x16x32_bf16 v[70:73], v[188:191], v[240:243], v[70:73]
	v_mfma_f32_16x16x32_bf16 v[66:69], v[208:211], v[240:243], v[66:69]
	s_setprio 0
	s_barrier
	s_add_i32 s18, s18, s30
	v_lshl_add_u64 v[158:159], s[4:5], 0, v[134:135]
	s_mov_b32 m0, s18
	ds_read_b128 v[212:215], v170 offset:16384
	ds_read_b128 v[216:219], v170 offset:17408
	ds_read_b128 v[220:223], v170 offset:18432
	ds_read_b128 v[224:227], v170 offset:19456
	ds_read_b128 v[228:231], v170 offset:20480
	ds_read_b128 v[232:235], v170 offset:21504
	ds_read_b128 v[236:239], v170 offset:22528
	ds_read_b128 v[240:243], v170 offset:23552
	global_load_lds_dwordx4 v[158:159], off
	s_add_i32 m0, s18, 0x2000
	s_add_u32 s18, s4, 0x40000
	v_lshl_add_u64 v[244:245], s[4:5], 0, v[130:131]
	s_addc_u32 s19, s5, 0
	s_add_i32 s20, s20, s30
	global_load_lds_dwordx4 v[244:245], off
	s_mov_b32 m0, s20
	v_lshl_add_u64 v[248:249], s[38:39], 0, v[132:133]
	global_load_lds_dwordx4 v134, s[18:19]
	s_add_i32 m0, s20, 0x2000
	s_nop 0
	global_load_lds_dwordx4 v130, s[18:19]
	v_lshl_add_u64 v[246:247], s[38:39], 0, v[136:137]
	s_mov_b32 m0, s31
	s_nop 0
	global_load_lds_dwordx4 v[246:247], off
	s_mov_b32 m0, s84
	s_nop 0
	global_load_lds_dwordx4 v[248:249], off
	s_waitcnt vmcnt(8)
	s_waitcnt lgkmcnt(0)
	s_barrier
	s_setprio 1
	s_waitcnt lgkmcnt(0)
	v_mfma_f32_16x16x32_bf16 v[62:65], v[154:157], v[212:215], v[62:65]
	v_mfma_f32_16x16x32_bf16 v[58:61], v[176:179], v[212:215], v[58:61]
	v_mfma_f32_16x16x32_bf16 v[46:49], v[154:157], v[220:223], v[46:49]
	v_mfma_f32_16x16x32_bf16 v[42:45], v[176:179], v[220:223], v[42:45]
	v_mfma_f32_16x16x32_bf16 v[30:33], v[154:157], v[228:231], v[30:33]
	v_mfma_f32_16x16x32_bf16 v[26:29], v[176:179], v[228:231], v[26:29]
	v_mfma_f32_16x16x32_bf16 v[14:17], v[154:157], v[236:239], v[14:17]
	v_mfma_f32_16x16x32_bf16 v[10:13], v[176:179], v[236:239], v[10:13]
	v_mfma_f32_16x16x32_bf16 v[62:65], v[172:175], v[216:219], v[62:65]
	v_mfma_f32_16x16x32_bf16 v[58:61], v[180:183], v[216:219], v[58:61]
	v_mfma_f32_16x16x32_bf16 v[46:49], v[172:175], v[224:227], v[46:49]
	v_mfma_f32_16x16x32_bf16 v[42:45], v[180:183], v[224:227], v[42:45]
	v_mfma_f32_16x16x32_bf16 v[30:33], v[172:175], v[232:235], v[30:33]
	v_mfma_f32_16x16x32_bf16 v[26:29], v[180:183], v[232:235], v[26:29]
	v_mfma_f32_16x16x32_bf16 v[14:17], v[172:175], v[240:243], v[14:17]
	v_mfma_f32_16x16x32_bf16 v[10:13], v[180:183], v[240:243], v[10:13]
	s_setprio 0
	s_setprio 1
	v_mfma_f32_16x16x32_bf16 v[54:57], v[184:187], v[212:215], v[54:57]
	v_mfma_f32_16x16x32_bf16 v[50:53], v[204:207], v[212:215], v[50:53]
	v_mfma_f32_16x16x32_bf16 v[38:41], v[184:187], v[220:223], v[38:41]
	v_mfma_f32_16x16x32_bf16 v[34:37], v[204:207], v[220:223], v[34:37]
	v_mfma_f32_16x16x32_bf16 v[22:25], v[184:187], v[228:231], v[22:25]
	v_mfma_f32_16x16x32_bf16 v[18:21], v[204:207], v[228:231], v[18:21]
	v_mfma_f32_16x16x32_bf16 v[6:9], v[184:187], v[236:239], v[6:9]
	v_mfma_f32_16x16x32_bf16 v[2:5], v[204:207], v[236:239], v[2:5]
	v_mfma_f32_16x16x32_bf16 v[54:57], v[188:191], v[216:219], v[54:57]
	v_mfma_f32_16x16x32_bf16 v[50:53], v[208:211], v[216:219], v[50:53]
	v_mfma_f32_16x16x32_bf16 v[38:41], v[188:191], v[224:227], v[38:41]
	v_mfma_f32_16x16x32_bf16 v[34:37], v[208:211], v[224:227], v[34:37]
	v_mfma_f32_16x16x32_bf16 v[22:25], v[188:191], v[232:235], v[22:25]
	v_mfma_f32_16x16x32_bf16 v[18:21], v[208:211], v[232:235], v[18:21]
	v_mfma_f32_16x16x32_bf16 v[6:9], v[188:191], v[240:243], v[6:9]
	v_mfma_f32_16x16x32_bf16 v[2:5], v[208:211], v[240:243], v[2:5]
	s_setprio 0
	s_barrier
	s_add_i32 s20, 0, 0x18000
	v_add_u32_e32 v0, s20, v161
	s_add_i32 s12, 0, 0x1c000
	ds_read_b128 v[154:157], v0
	ds_read_b128 v[172:175], v0 offset:1024
	ds_read_b128 v[176:179], v0 offset:2048
	ds_read_b128 v[180:183], v0 offset:3072
	v_add_u32_e32 v0, s12, v161
	ds_read_b128 v[184:187], v0
	ds_read_b128 v[188:191], v0 offset:1024
	ds_read_b128 v[204:207], v0 offset:2048
	ds_read_b128 v[208:211], v0 offset:3072
	s_add_u32 s18, s38, 0x40000
	s_addc_u32 s19, s39, 0
	s_mov_b32 m0, s85
	ds_read_b128 v[212:215], v170 offset:32768
	ds_read_b128 v[216:219], v170 offset:33792
	ds_read_b128 v[220:223], v170 offset:34816
	ds_read_b128 v[224:227], v170 offset:35840
	ds_read_b128 v[228:231], v170 offset:36864
	ds_read_b128 v[232:235], v170 offset:37888
	ds_read_b128 v[236:239], v170 offset:38912
	ds_read_b128 v[240:243], v170 offset:39936
	global_load_lds_dwordx4 v136, s[18:19]
	v_lshl_add_u64 v[250:251], s[18:19], 0, v[132:133]
	s_mov_b32 m0, s86
	s_nop 0
	global_load_lds_dwordx4 v[250:251], off
	s_waitcnt vmcnt(8)
	s_waitcnt lgkmcnt(0)
	s_barrier
	s_setprio 1
	s_waitcnt lgkmcnt(0)
	v_mfma_f32_16x16x32_bf16 v[126:129], v[154:157], v[212:215], v[126:129]
	v_mfma_f32_16x16x32_bf16 v[122:125], v[176:179], v[212:215], v[122:125]
	v_mfma_f32_16x16x32_bf16 v[110:113], v[154:157], v[220:223], v[110:113]
	v_mfma_f32_16x16x32_bf16 v[106:109], v[176:179], v[220:223], v[106:109]
	v_mfma_f32_16x16x32_bf16 v[94:97], v[154:157], v[228:231], v[94:97]
	v_mfma_f32_16x16x32_bf16 v[90:93], v[176:179], v[228:231], v[90:93]
	v_mfma_f32_16x16x32_bf16 v[78:81], v[154:157], v[236:239], v[78:81]
	v_mfma_f32_16x16x32_bf16 v[74:77], v[176:179], v[236:239], v[74:77]
	v_mfma_f32_16x16x32_bf16 v[126:129], v[172:175], v[216:219], v[126:129]
	v_mfma_f32_16x16x32_bf16 v[122:125], v[180:183], v[216:219], v[122:125]
	v_mfma_f32_16x16x32_bf16 v[110:113], v[172:175], v[224:227], v[110:113]
	v_mfma_f32_16x16x32_bf16 v[106:109], v[180:183], v[224:227], v[106:109]
	v_mfma_f32_16x16x32_bf16 v[94:97], v[172:175], v[232:235], v[94:97]
	v_mfma_f32_16x16x32_bf16 v[90:93], v[180:183], v[232:235], v[90:93]
	v_mfma_f32_16x16x32_bf16 v[78:81], v[172:175], v[240:243], v[78:81]
	v_mfma_f32_16x16x32_bf16 v[74:77], v[180:183], v[240:243], v[74:77]
	s_setprio 0
	s_setprio 1
	v_mfma_f32_16x16x32_bf16 v[118:121], v[184:187], v[212:215], v[118:121]
	v_mfma_f32_16x16x32_bf16 v[114:117], v[204:207], v[212:215], v[114:117]
	v_mfma_f32_16x16x32_bf16 v[102:105], v[184:187], v[220:223], v[102:105]
	v_mfma_f32_16x16x32_bf16 v[98:101], v[204:207], v[220:223], v[98:101]
	v_mfma_f32_16x16x32_bf16 v[86:89], v[184:187], v[228:231], v[86:89]
	v_mfma_f32_16x16x32_bf16 v[82:85], v[204:207], v[228:231], v[82:85]
	v_mfma_f32_16x16x32_bf16 v[70:73], v[184:187], v[236:239], v[70:73]
	v_mfma_f32_16x16x32_bf16 v[66:69], v[204:207], v[236:239], v[66:69]
	v_mfma_f32_16x16x32_bf16 v[118:121], v[188:191], v[216:219], v[118:121]
	v_mfma_f32_16x16x32_bf16 v[114:117], v[208:211], v[216:219], v[114:117]
	v_mfma_f32_16x16x32_bf16 v[102:105], v[188:191], v[224:227], v[102:105]
	v_mfma_f32_16x16x32_bf16 v[98:101], v[208:211], v[224:227], v[98:101]
	v_mfma_f32_16x16x32_bf16 v[86:89], v[188:191], v[232:235], v[86:89]
	v_mfma_f32_16x16x32_bf16 v[82:85], v[208:211], v[232:235], v[82:85]
	v_mfma_f32_16x16x32_bf16 v[70:73], v[188:191], v[240:243], v[70:73]
	v_mfma_f32_16x16x32_bf16 v[66:69], v[208:211], v[240:243], v[66:69]
	s_setprio 0
	s_barrier
	s_add_i32 s13, s20, s30
	v_lshl_add_u64 v[158:159], v[158:159], 0, s[14:15]
	s_mov_b32 m0, s13
	ds_read_b128 v[212:215], v170 offset:49152
	ds_read_b128 v[216:219], v170 offset:50176
	ds_read_b128 v[220:223], v170 offset:51200
	ds_read_b128 v[224:227], v170 offset:52224
	ds_read_b128 v[228:231], v170 offset:53248
	ds_read_b128 v[232:235], v170 offset:54272
	ds_read_b128 v[236:239], v170 offset:55296
	ds_read_b128 v[240:243], v170 offset:56320
	global_load_lds_dwordx4 v[158:159], off
	s_add_i32 m0, s13, 0x2000
	s_add_u32 s4, s4, 0x40080
	v_lshl_add_u64 v[158:159], v[244:245], 0, s[14:15]
	s_addc_u32 s5, s5, 0
	s_add_i32 s12, s12, s30
	global_load_lds_dwordx4 v[158:159], off
	s_mov_b32 m0, s12
	s_nop 0
	global_load_lds_dwordx4 v134, s[4:5]
	s_add_i32 m0, s12, 0x2000
	s_nop 0
	global_load_lds_dwordx4 v130, s[4:5]
	v_lshl_add_u64 v[158:159], v[246:247], 0, s[14:15]
	s_mov_b32 m0, s87
	s_nop 0
	global_load_lds_dwordx4 v[158:159], off
	v_lshl_add_u64 v[158:159], v[248:249], 0, s[14:15]
	s_mov_b32 m0, s68
	s_nop 0
	global_load_lds_dwordx4 v[158:159], off
	s_waitcnt vmcnt(8)
	s_waitcnt lgkmcnt(0)
	s_barrier
	s_setprio 1
	s_waitcnt lgkmcnt(0)
	v_mfma_f32_16x16x32_bf16 v[62:65], v[154:157], v[212:215], v[62:65]
	v_mfma_f32_16x16x32_bf16 v[58:61], v[176:179], v[212:215], v[58:61]
	v_mfma_f32_16x16x32_bf16 v[46:49], v[154:157], v[220:223], v[46:49]
	v_mfma_f32_16x16x32_bf16 v[42:45], v[176:179], v[220:223], v[42:45]
	v_mfma_f32_16x16x32_bf16 v[30:33], v[154:157], v[228:231], v[30:33]
	v_mfma_f32_16x16x32_bf16 v[26:29], v[176:179], v[228:231], v[26:29]
	v_mfma_f32_16x16x32_bf16 v[14:17], v[154:157], v[236:239], v[14:17]
	v_mfma_f32_16x16x32_bf16 v[10:13], v[176:179], v[236:239], v[10:13]
	v_mfma_f32_16x16x32_bf16 v[62:65], v[172:175], v[216:219], v[62:65]
	v_mfma_f32_16x16x32_bf16 v[58:61], v[180:183], v[216:219], v[58:61]
	v_mfma_f32_16x16x32_bf16 v[46:49], v[172:175], v[224:227], v[46:49]
	v_mfma_f32_16x16x32_bf16 v[42:45], v[180:183], v[224:227], v[42:45]
	v_mfma_f32_16x16x32_bf16 v[30:33], v[172:175], v[232:235], v[30:33]
	v_mfma_f32_16x16x32_bf16 v[26:29], v[180:183], v[232:235], v[26:29]
	v_mfma_f32_16x16x32_bf16 v[14:17], v[172:175], v[240:243], v[14:17]
	v_mfma_f32_16x16x32_bf16 v[10:13], v[180:183], v[240:243], v[10:13]
	s_setprio 0
	s_setprio 1
	v_mfma_f32_16x16x32_bf16 v[54:57], v[184:187], v[212:215], v[54:57]
	v_mfma_f32_16x16x32_bf16 v[50:53], v[204:207], v[212:215], v[50:53]
	v_mfma_f32_16x16x32_bf16 v[38:41], v[184:187], v[220:223], v[38:41]
	v_mfma_f32_16x16x32_bf16 v[34:37], v[204:207], v[220:223], v[34:37]
	v_mfma_f32_16x16x32_bf16 v[22:25], v[184:187], v[228:231], v[22:25]
	v_mfma_f32_16x16x32_bf16 v[18:21], v[204:207], v[228:231], v[18:21]
	v_mfma_f32_16x16x32_bf16 v[6:9], v[184:187], v[236:239], v[6:9]
	v_mfma_f32_16x16x32_bf16 v[2:5], v[204:207], v[236:239], v[2:5]
	v_mfma_f32_16x16x32_bf16 v[54:57], v[188:191], v[216:219], v[54:57]
	v_mfma_f32_16x16x32_bf16 v[50:53], v[208:211], v[216:219], v[50:53]
	v_mfma_f32_16x16x32_bf16 v[38:41], v[188:191], v[224:227], v[38:41]
	v_mfma_f32_16x16x32_bf16 v[34:37], v[208:211], v[224:227], v[34:37]
	v_mfma_f32_16x16x32_bf16 v[22:25], v[188:191], v[232:235], v[22:25]
	v_mfma_f32_16x16x32_bf16 v[18:21], v[208:211], v[232:235], v[18:21]
	v_mfma_f32_16x16x32_bf16 v[6:9], v[188:191], v[240:243], v[6:9]
	v_mfma_f32_16x16x32_bf16 v[2:5], v[208:211], v[240:243], v[2:5]
	s_setprio 0
	s_barrier
	s_add_i32 s77, s77, 2
	s_add_u32 s0, s0, 0x100
	s_addc_u32 s1, s1, 0
	s_add_u32 vcc_lo, vcc_lo, 0x100
	s_addc_u32 vcc_hi, vcc_hi, 0
	s_cmp_gt_u32 s77, 13
	s_cbranch_scc0 .LBB0_151
	s_and_b64 vcc, exec, s[48:49]
	s_cbranch_vccz .LBB0_154
	s_barrier

.LBB0_1295:
	s_add_u32 s6, s6, 0x9504000
	s_addc_u32 s7, s7, 0
	s_lshl_b32 s1, s1, 5
	s_and_b32 s1, s1, 0x60
	s_add_i32 m0, s66, 0x18000
	v_lshl_add_u64 v[8:9], v[8:9], 0, s[14:15]
	s_lshl_b32 s12, s0, 13
	s_lshl_b32 s13, s1, 7
	s_waitcnt vmcnt(2)
	s_barrier
	global_load_lds_dwordx4 v[8:9], off
	v_lshl_add_u64 v[6:7], v[6:7], 0, s[14:15]
	s_add_i32 m0, s66, 0x1a000
	s_add_i32 s80, s66, 0x8000
	s_add_i32 s81, s66, 0xa000
	global_load_lds_dwordx4 v[6:7], off
	v_lshl_add_u64 v[2:3], v[2:3], 0, s[14:15]
	s_mov_b32 m0, s80
	s_add_u32 s18, s50, 0x40080
	global_load_lds_dwordx4 v[2:3], off
	v_lshl_add_u64 v[2:3], v[4:5], 0, s[14:15]
	s_mov_b32 m0, s81
	s_addc_u32 s19, s51, 0
	global_load_lds_dwordx4 v[2:3], off
	s_add_i32 m0, s66, 0x1c000
	s_nop 0
	global_load_lds_dwordx4 v134, s[18:19]
	v_lshl_add_u64 v[2:3], s[18:19], 0, v[130:131]
	s_add_i32 m0, s66, 0x1e000
	s_cmpk_lt_u32 s8, 0x100
	global_load_lds_dwordx4 v[2:3], off
	v_lshrrev_b32_e32 v2, 1, v0
	v_and_b32_e32 v2, 24, v2
	v_and_b32_e32 v3, 15, v0
	v_lshlrev_b32_e32 v4, 1, v2
	v_lshlrev_b32_e32 v0, 2, v0
	v_lshl_or_b32 v154, s0, 6, v3
	v_lshl_or_b32 v3, v3, 6, v4
	v_and_b32_e32 v0, 32, v0
	v_bitop3_b32 v4, v3, s12, v0 bitop3:0xde
	v_bitop3_b32 v155, v3, s13, v0 bitop3:0xde
	v_lshlrev_b32_e32 v0, 14, v14
	v_and_b32_e32 v0, 0xffff8000, v0
	v_lshl_add_u32 v0, v13, 11, v0
	v_and_b32_e32 v3, 1, v14
	v_lshl_or_b32 v0, v3, 6, v0
	v_lshl_add_u32 v150, v15, 1, v0
	v_lshlrev_b32_e32 v0, 14, v10
	v_and_b32_e32 v0, 0xffff8000, v0
	s_waitcnt vmcnt(6)
	v_lshl_add_u32 v0, v11, 11, v0
	v_and_b32_e32 v3, 1, v10
	s_cselect_b64 s[36:37], -1, 0
	v_lshl_or_b32 v0, v3, 6, v0
	s_lshl_b32 s8, s1, 1
	v_readlane_b32 s0, v254, 1
	v_mov_b32_e32 v151, v1
	v_lshl_add_u32 v152, v12, 1, v0
	v_mov_b32_e32 v153, v1
	s_mov_b32 s82, 0
	v_add_u32_e32 v156, 0, v4
	v_lshlrev_b32_e32 v0, 1, v2
	v_readlane_b32 s83, v253, 60
	s_mov_b32 s84, s0
	s_barrier
	v_readlane_b32 s1, v254, 2
	s_branch .LBB0_1298

.LBB0_1301:
	s_add_u32 s12, s48, 0xfffc0080
	s_addc_u32 s13, s49, -1
	s_add_i32 s18, 0, 0x10000
	s_cmp_eq_u32 s77, 12
	s_cselect_b32 s79, s43, s13
	s_cselect_b32 s78, s85, s12
	v_add_u32_e32 v157, s18, v155
	s_cselect_b32 s51, s39, s96
	s_cselect_b32 s50, s86, s87
	s_add_i32 s12, 0, 0x14000
	ds_read_b128 v[158:161], v157
	ds_read_b128 v[162:165], v157 offset:1024
	ds_read_b128 v[166:169], v157 offset:2048
	ds_read_b128 v[170:173], v157 offset:3072
	v_add_u32_e32 v157, s12, v155
	ds_read_b128 v[174:177], v157
	ds_read_b128 v[178:181], v157 offset:1024
	ds_read_b128 v[182:185], v157 offset:2048
	ds_read_b128 v[186:189], v157 offset:3072
	v_lshl_add_u64 v[190:191], s[48:49], 0, v[150:151]
	s_add_i32 m0, s66, 0xc000
	ds_read_b128 v[204:207], v156
	ds_read_b128 v[208:211], v156 offset:1024
	ds_read_b128 v[212:215], v156 offset:2048
	ds_read_b128 v[216:219], v156 offset:3072
	ds_read_b128 v[220:223], v156 offset:4096
	ds_read_b128 v[224:227], v156 offset:5120
	ds_read_b128 v[228:231], v156 offset:6144
	ds_read_b128 v[232:235], v156 offset:7168
	global_load_lds_dwordx4 v[190:191], off
	v_lshl_add_u64 v[190:191], s[48:49], 0, v[152:153]
	s_add_i32 m0, s66, 0xe000
	s_nop 0
	global_load_lds_dwordx4 v[190:191], off
	s_waitcnt vmcnt(8)
	s_waitcnt lgkmcnt(0)
	s_barrier
	s_setprio 1
	s_waitcnt lgkmcnt(0)
	v_mfma_f32_16x16x32_bf16 v[126:129], v[158:161], v[204:207], v[126:129]
	v_mfma_f32_16x16x32_bf16 v[122:125], v[166:169], v[204:207], v[122:125]
	v_mfma_f32_16x16x32_bf16 v[110:113], v[158:161], v[212:215], v[110:113]
	v_mfma_f32_16x16x32_bf16 v[106:109], v[166:169], v[212:215], v[106:109]
	v_mfma_f32_16x16x32_bf16 v[94:97], v[158:161], v[220:223], v[94:97]
	v_mfma_f32_16x16x32_bf16 v[90:93], v[166:169], v[220:223], v[90:93]
	v_mfma_f32_16x16x32_bf16 v[78:81], v[158:161], v[228:231], v[78:81]
	v_mfma_f32_16x16x32_bf16 v[74:77], v[166:169], v[228:231], v[74:77]
	v_mfma_f32_16x16x32_bf16 v[126:129], v[162:165], v[208:211], v[126:129]
	v_mfma_f32_16x16x32_bf16 v[122:125], v[170:173], v[208:211], v[122:125]
	v_mfma_f32_16x16x32_bf16 v[110:113], v[162:165], v[216:219], v[110:113]
	v_mfma_f32_16x16x32_bf16 v[106:109], v[170:173], v[216:219], v[106:109]
	v_mfma_f32_16x16x32_bf16 v[94:97], v[162:165], v[224:227], v[94:97]
	v_mfma_f32_16x16x32_bf16 v[90:93], v[170:173], v[224:227], v[90:93]
	v_mfma_f32_16x16x32_bf16 v[78:81], v[162:165], v[232:235], v[78:81]
	v_mfma_f32_16x16x32_bf16 v[74:77], v[170:173], v[232:235], v[74:77]
	s_setprio 0
	s_setprio 1
	v_mfma_f32_16x16x32_bf16 v[118:121], v[174:177], v[204:207], v[118:121]
	v_mfma_f32_16x16x32_bf16 v[114:117], v[182:185], v[204:207], v[114:117]
	v_mfma_f32_16x16x32_bf16 v[102:105], v[174:177], v[212:215], v[102:105]
	v_mfma_f32_16x16x32_bf16 v[98:101], v[182:185], v[212:215], v[98:101]
	v_mfma_f32_16x16x32_bf16 v[86:89], v[174:177], v[220:223], v[86:89]
	v_mfma_f32_16x16x32_bf16 v[82:85], v[182:185], v[220:223], v[82:85]
	v_mfma_f32_16x16x32_bf16 v[70:73], v[174:177], v[228:231], v[70:73]
	v_mfma_f32_16x16x32_bf16 v[66:69], v[182:185], v[228:231], v[66:69]
	v_mfma_f32_16x16x32_bf16 v[118:121], v[178:181], v[208:211], v[118:121]
	v_mfma_f32_16x16x32_bf16 v[114:117], v[186:189], v[208:211], v[114:117]
	v_mfma_f32_16x16x32_bf16 v[102:105], v[178:181], v[216:219], v[102:105]
	v_mfma_f32_16x16x32_bf16 v[98:101], v[186:189], v[216:219], v[98:101]
	v_mfma_f32_16x16x32_bf16 v[86:89], v[178:181], v[224:227], v[86:89]
	v_mfma_f32_16x16x32_bf16 v[82:85], v[186:189], v[224:227], v[82:85]
	v_mfma_f32_16x16x32_bf16 v[70:73], v[178:181], v[232:235], v[70:73]
	v_mfma_f32_16x16x32_bf16 v[66:69], v[186:189], v[232:235], v[66:69]
	s_setprio 0
	s_barrier
	s_add_i32 s13, s18, s31
	v_lshl_add_u64 v[190:191], s[50:51], 0, v[134:135]
	s_mov_b32 m0, s13
	ds_read_b128 v[204:207], v156 offset:16384
	ds_read_b128 v[208:211], v156 offset:17408
	ds_read_b128 v[212:215], v156 offset:18432
	ds_read_b128 v[216:219], v156 offset:19456
	ds_read_b128 v[220:223], v156 offset:20480
	ds_read_b128 v[224:227], v156 offset:21504
	ds_read_b128 v[228:231], v156 offset:22528
	ds_read_b128 v[232:235], v156 offset:23552
	global_load_lds_dwordx4 v[190:191], off
	s_add_i32 m0, s13, 0x2000
	s_add_u32 s18, s50, 0x40000
	v_lshl_add_u64 v[236:237], s[50:51], 0, v[130:131]
	s_addc_u32 s19, s51, 0
	s_add_i32 s12, s12, s31
	global_load_lds_dwordx4 v[236:237], off
	s_mov_b32 m0, s12
	v_lshl_add_u64 v[240:241], s[78:79], 0, v[132:133]
	global_load_lds_dwordx4 v134, s[18:19]
	s_add_i32 m0, s12, 0x2000
	s_nop 0
	global_load_lds_dwordx4 v130, s[18:19]
	v_lshl_add_u64 v[238:239], s[78:79], 0, v[136:137]
	s_mov_b32 m0, s66
	s_nop 0
	global_load_lds_dwordx4 v[238:239], off
	s_mov_b32 m0, s67
	s_nop 0
	global_load_lds_dwordx4 v[240:241], off
	s_waitcnt vmcnt(8)
	s_waitcnt lgkmcnt(0)
	s_barrier
	s_setprio 1
	s_waitcnt lgkmcnt(0)
	v_mfma_f32_16x16x32_bf16 v[62:65], v[158:161], v[204:207], v[62:65]
	v_mfma_f32_16x16x32_bf16 v[58:61], v[166:169], v[204:207], v[58:61]
	v_mfma_f32_16x16x32_bf16 v[46:49], v[158:161], v[212:215], v[46:49]
	v_mfma_f32_16x16x32_bf16 v[42:45], v[166:169], v[212:215], v[42:45]
	v_mfma_f32_16x16x32_bf16 v[30:33], v[158:161], v[220:223], v[30:33]
	v_mfma_f32_16x16x32_bf16 v[26:29], v[166:169], v[220:223], v[26:29]
	v_mfma_f32_16x16x32_bf16 v[14:17], v[158:161], v[228:231], v[14:17]
	v_mfma_f32_16x16x32_bf16 v[10:13], v[166:169], v[228:231], v[10:13]
	v_mfma_f32_16x16x32_bf16 v[62:65], v[162:165], v[208:211], v[62:65]
	v_mfma_f32_16x16x32_bf16 v[58:61], v[170:173], v[208:211], v[58:61]
	v_mfma_f32_16x16x32_bf16 v[46:49], v[162:165], v[216:219], v[46:49]
	v_mfma_f32_16x16x32_bf16 v[42:45], v[170:173], v[216:219], v[42:45]
	v_mfma_f32_16x16x32_bf16 v[30:33], v[162:165], v[224:227], v[30:33]
	v_mfma_f32_16x16x32_bf16 v[26:29], v[170:173], v[224:227], v[26:29]
	v_mfma_f32_16x16x32_bf16 v[14:17], v[162:165], v[232:235], v[14:17]
	v_mfma_f32_16x16x32_bf16 v[10:13], v[170:173], v[232:235], v[10:13]
	s_setprio 0
	s_setprio 1
	v_mfma_f32_16x16x32_bf16 v[54:57], v[174:177], v[204:207], v[54:57]
	v_mfma_f32_16x16x32_bf16 v[50:53], v[182:185], v[204:207], v[50:53]
	v_mfma_f32_16x16x32_bf16 v[38:41], v[174:177], v[212:215], v[38:41]
	v_mfma_f32_16x16x32_bf16 v[34:37], v[182:185], v[212:215], v[34:37]
	v_mfma_f32_16x16x32_bf16 v[22:25], v[174:177], v[220:223], v[22:25]
	v_mfma_f32_16x16x32_bf16 v[18:21], v[182:185], v[220:223], v[18:21]
	v_mfma_f32_16x16x32_bf16 v[6:9], v[174:177], v[228:231], v[6:9]
	v_mfma_f32_16x16x32_bf16 v[2:5], v[182:185], v[228:231], v[2:5]
	v_mfma_f32_16x16x32_bf16 v[54:57], v[178:181], v[208:211], v[54:57]
	v_mfma_f32_16x16x32_bf16 v[50:53], v[186:189], v[208:211], v[50:53]
	v_mfma_f32_16x16x32_bf16 v[38:41], v[178:181], v[216:219], v[38:41]
	v_mfma_f32_16x16x32_bf16 v[34:37], v[186:189], v[216:219], v[34:37]
	v_mfma_f32_16x16x32_bf16 v[22:25], v[178:181], v[224:227], v[22:25]
	v_mfma_f32_16x16x32_bf16 v[18:21], v[186:189], v[224:227], v[18:21]
	v_mfma_f32_16x16x32_bf16 v[6:9], v[178:181], v[232:235], v[6:9]
	v_mfma_f32_16x16x32_bf16 v[2:5], v[186:189], v[232:235], v[2:5]
	s_setprio 0
	s_barrier
	s_add_i32 s12, 0, 0x18000
	v_add_u32_e32 v157, s12, v155
	s_add_i32 s13, 0, 0x1c000
	ds_read_b128 v[158:161], v157
	ds_read_b128 v[162:165], v157 offset:1024
	ds_read_b128 v[166:169], v157 offset:2048
	ds_read_b128 v[170:173], v157 offset:3072
	v_add_u32_e32 v157, s13, v155
	ds_read_b128 v[174:177], v157
	ds_read_b128 v[178:181], v157 offset:1024
	ds_read_b128 v[182:185], v157 offset:2048
	ds_read_b128 v[186:189], v157 offset:3072
	s_add_u32 s18, s78, 0x40000
	s_addc_u32 s19, s79, 0
	s_mov_b32 m0, s68
	ds_read_b128 v[204:207], v156 offset:32768
	ds_read_b128 v[208:211], v156 offset:33792
	ds_read_b128 v[212:215], v156 offset:34816
	ds_read_b128 v[216:219], v156 offset:35840
	ds_read_b128 v[220:223], v156 offset:36864
	ds_read_b128 v[224:227], v156 offset:37888
	ds_read_b128 v[228:231], v156 offset:38912
	ds_read_b128 v[232:235], v156 offset:39936
	global_load_lds_dwordx4 v136, s[18:19]
	v_lshl_add_u64 v[242:243], s[18:19], 0, v[132:133]
	s_mov_b32 m0, s70
	s_nop 0
	global_load_lds_dwordx4 v[242:243], off
	s_waitcnt vmcnt(8)
	s_waitcnt lgkmcnt(0)
	s_barrier
	s_setprio 1
	s_waitcnt lgkmcnt(0)
	v_mfma_f32_16x16x32_bf16 v[126:129], v[158:161], v[204:207], v[126:129]
	v_mfma_f32_16x16x32_bf16 v[122:125], v[166:169], v[204:207], v[122:125]
	v_mfma_f32_16x16x32_bf16 v[110:113], v[158:161], v[212:215], v[110:113]
	v_mfma_f32_16x16x32_bf16 v[106:109], v[166:169], v[212:215], v[106:109]
	v_mfma_f32_16x16x32_bf16 v[94:97], v[158:161], v[220:223], v[94:97]
	v_mfma_f32_16x16x32_bf16 v[90:93], v[166:169], v[220:223], v[90:93]
	v_mfma_f32_16x16x32_bf16 v[78:81], v[158:161], v[228:231], v[78:81]
	v_mfma_f32_16x16x32_bf16 v[74:77], v[166:169], v[228:231], v[74:77]
	v_mfma_f32_16x16x32_bf16 v[126:129], v[162:165], v[208:211], v[126:129]
	v_mfma_f32_16x16x32_bf16 v[122:125], v[170:173], v[208:211], v[122:125]
	v_mfma_f32_16x16x32_bf16 v[110:113], v[162:165], v[216:219], v[110:113]
	v_mfma_f32_16x16x32_bf16 v[106:109], v[170:173], v[216:219], v[106:109]
	v_mfma_f32_16x16x32_bf16 v[94:97], v[162:165], v[224:227], v[94:97]
	v_mfma_f32_16x16x32_bf16 v[90:93], v[170:173], v[224:227], v[90:93]
	v_mfma_f32_16x16x32_bf16 v[78:81], v[162:165], v[232:235], v[78:81]
	v_mfma_f32_16x16x32_bf16 v[74:77], v[170:173], v[232:235], v[74:77]
	s_setprio 0
	s_setprio 1
	v_mfma_f32_16x16x32_bf16 v[118:121], v[174:177], v[204:207], v[118:121]
	v_mfma_f32_16x16x32_bf16 v[114:117], v[182:185], v[204:207], v[114:117]
	v_mfma_f32_16x16x32_bf16 v[102:105], v[174:177], v[212:215], v[102:105]
	v_mfma_f32_16x16x32_bf16 v[98:101], v[182:185], v[212:215], v[98:101]
	v_mfma_f32_16x16x32_bf16 v[86:89], v[174:177], v[220:223], v[86:89]
	v_mfma_f32_16x16x32_bf16 v[82:85], v[182:185], v[220:223], v[82:85]
	v_mfma_f32_16x16x32_bf16 v[70:73], v[174:177], v[228:231], v[70:73]
	v_mfma_f32_16x16x32_bf16 v[66:69], v[182:185], v[228:231], v[66:69]
	v_mfma_f32_16x16x32_bf16 v[118:121], v[178:181], v[208:211], v[118:121]
	v_mfma_f32_16x16x32_bf16 v[114:117], v[186:189], v[208:211], v[114:117]
	v_mfma_f32_16x16x32_bf16 v[102:105], v[178:181], v[216:219], v[102:105]
	v_mfma_f32_16x16x32_bf16 v[98:101], v[186:189], v[216:219], v[98:101]
	v_mfma_f32_16x16x32_bf16 v[86:89], v[178:181], v[224:227], v[86:89]
	v_mfma_f32_16x16x32_bf16 v[82:85], v[186:189], v[224:227], v[82:85]
	v_mfma_f32_16x16x32_bf16 v[70:73], v[178:181], v[232:235], v[70:73]
	v_mfma_f32_16x16x32_bf16 v[66:69], v[186:189], v[232:235], v[66:69]
	s_setprio 0
	s_barrier
	s_add_i32 s12, s12, s31
	v_lshl_add_u64 v[190:191], v[190:191], 0, s[14:15]
	s_mov_b32 m0, s12
	ds_read_b128 v[204:207], v156 offset:49152
	ds_read_b128 v[208:211], v156 offset:50176
	ds_read_b128 v[212:215], v156 offset:51200
	ds_read_b128 v[216:219], v156 offset:52224
	ds_read_b128 v[220:223], v156 offset:53248
	ds_read_b128 v[224:227], v156 offset:54272
	ds_read_b128 v[228:231], v156 offset:55296
	ds_read_b128 v[232:235], v156 offset:56320
	global_load_lds_dwordx4 v[190:191], off
	s_add_i32 m0, s12, 0x2000
	s_add_u32 s18, s50, 0x40080
	v_lshl_add_u64 v[190:191], v[236:237], 0, s[14:15]
	s_addc_u32 s19, s51, 0
	s_add_i32 s12, s13, s31
	global_load_lds_dwordx4 v[190:191], off
	s_mov_b32 m0, s12
	s_nop 0
	global_load_lds_dwordx4 v134, s[18:19]
	s_add_i32 m0, s12, 0x2000
	s_nop 0
	global_load_lds_dwordx4 v130, s[18:19]
	v_lshl_add_u64 v[190:191], v[238:239], 0, s[14:15]
	s_mov_b32 m0, s80
	s_nop 0
	global_load_lds_dwordx4 v[190:191], off
	v_lshl_add_u64 v[190:191], v[240:241], 0, s[14:15]
	s_mov_b32 m0, s81
	s_nop 0
	global_load_lds_dwordx4 v[190:191], off
	s_waitcnt vmcnt(8)
	s_waitcnt lgkmcnt(0)
	s_barrier
	s_setprio 1
	s_waitcnt lgkmcnt(0)
	v_mfma_f32_16x16x32_bf16 v[62:65], v[158:161], v[204:207], v[62:65]
	v_mfma_f32_16x16x32_bf16 v[58:61], v[166:169], v[204:207], v[58:61]
	v_mfma_f32_16x16x32_bf16 v[46:49], v[158:161], v[212:215], v[46:49]
	v_mfma_f32_16x16x32_bf16 v[42:45], v[166:169], v[212:215], v[42:45]
	v_mfma_f32_16x16x32_bf16 v[30:33], v[158:161], v[220:223], v[30:33]
	v_mfma_f32_16x16x32_bf16 v[26:29], v[166:169], v[220:223], v[26:29]
	v_mfma_f32_16x16x32_bf16 v[14:17], v[158:161], v[228:231], v[14:17]
	v_mfma_f32_16x16x32_bf16 v[10:13], v[166:169], v[228:231], v[10:13]
	v_mfma_f32_16x16x32_bf16 v[62:65], v[162:165], v[208:211], v[62:65]
	v_mfma_f32_16x16x32_bf16 v[58:61], v[170:173], v[208:211], v[58:61]
	v_mfma_f32_16x16x32_bf16 v[46:49], v[162:165], v[216:219], v[46:49]
	v_mfma_f32_16x16x32_bf16 v[42:45], v[170:173], v[216:219], v[42:45]
	v_mfma_f32_16x16x32_bf16 v[30:33], v[162:165], v[224:227], v[30:33]
	v_mfma_f32_16x16x32_bf16 v[26:29], v[170:173], v[224:227], v[26:29]
	v_mfma_f32_16x16x32_bf16 v[14:17], v[162:165], v[232:235], v[14:17]
	v_mfma_f32_16x16x32_bf16 v[10:13], v[170:173], v[232:235], v[10:13]
	s_setprio 0
	s_setprio 1
	v_mfma_f32_16x16x32_bf16 v[54:57], v[174:177], v[204:207], v[54:57]
	v_mfma_f32_16x16x32_bf16 v[50:53], v[182:185], v[204:207], v[50:53]
	v_mfma_f32_16x16x32_bf16 v[38:41], v[174:177], v[212:215], v[38:41]
	v_mfma_f32_16x16x32_bf16 v[34:37], v[182:185], v[212:215], v[34:37]
	v_mfma_f32_16x16x32_bf16 v[22:25], v[174:177], v[220:223], v[22:25]
	v_mfma_f32_16x16x32_bf16 v[18:21], v[182:185], v[220:223], v[18:21]
	v_mfma_f32_16x16x32_bf16 v[6:9], v[174:177], v[228:231], v[6:9]
	v_mfma_f32_16x16x32_bf16 v[2:5], v[182:185], v[228:231], v[2:5]
	v_mfma_f32_16x16x32_bf16 v[54:57], v[178:181], v[208:211], v[54:57]
	v_mfma_f32_16x16x32_bf16 v[50:53], v[186:189], v[208:211], v[50:53]
	v_mfma_f32_16x16x32_bf16 v[38:41], v[178:181], v[216:219], v[38:41]
	v_mfma_f32_16x16x32_bf16 v[34:37], v[186:189], v[216:219], v[34:37]
	v_mfma_f32_16x16x32_bf16 v[22:25], v[178:181], v[224:227], v[22:25]
	v_mfma_f32_16x16x32_bf16 v[18:21], v[186:189], v[224:227], v[18:21]
	v_mfma_f32_16x16x32_bf16 v[6:9], v[178:181], v[232:235], v[6:9]
	v_mfma_f32_16x16x32_bf16 v[2:5], v[186:189], v[232:235], v[2:5]
	s_setprio 0
	s_barrier
	s_add_i32 s77, s77, 2
	s_add_u32 s48, s48, 0x100
	s_addc_u32 s49, s49, 0
	s_add_u32 s87, s87, 0x100
	s_addc_u32 s96, s96, 0
	s_cmp_gt_u32 s77, 13
	s_cbranch_scc0 .LBB0_1301
	s_and_b64 vcc, exec, s[36:37]
	s_cbranch_vccz .LBB0_1304
	s_barrier

.LBB0_1378:
	s_add_u32 s48, s4, 0x100
	s_addc_u32 s49, s5, 0
	s_add_i32 s12, 0, 0x10000
	s_cmp_eq_u32 s77, 40
	s_cselect_b32 s79, s1, s49
	s_cselect_b32 s78, s0, s48
	s_cselect_b32 s51, s47, s87
	s_cselect_b32 s50, s46, s86
	s_add_i32 s13, 0, 0x14000
	v_add_u32_e32 v168, s12, v158
	v_add_u32_e32 v184, s13, v158
	ds_read_b128 v[154:157], v168
	ds_read_b128 v[160:163], v168 offset:1024
	ds_read_b128 v[164:167], v168 offset:2048
	ds_read_b128 v[168:171], v168 offset:3072
	ds_read_b128 v[172:175], v184
	ds_read_b128 v[176:179], v184 offset:1024
	ds_read_b128 v[180:183], v184 offset:2048
	ds_read_b128 v[184:187], v184 offset:3072
	v_lshl_add_u64 v[232:233], s[4:5], 0, v[150:151]
	s_add_i32 m0, s31, 0xc000
	ds_read_b128 v[188:191], v159
	ds_read_b128 v[204:207], v159 offset:1024
	ds_read_b128 v[208:211], v159 offset:2048
	ds_read_b128 v[212:215], v159 offset:3072
	ds_read_b128 v[216:219], v159 offset:4096
	ds_read_b128 v[220:223], v159 offset:5120
	ds_read_b128 v[224:227], v159 offset:6144
	ds_read_b128 v[228:231], v159 offset:7168
	global_load_lds_dwordx4 v[232:233], off
	v_lshl_add_u64 v[232:233], s[4:5], 0, v[152:153]
	s_add_i32 m0, s31, 0xe000
	s_nop 0
	global_load_lds_dwordx4 v[232:233], off
	s_waitcnt vmcnt(8)
	s_waitcnt lgkmcnt(0)
	s_barrier
	s_setprio 1
	s_waitcnt lgkmcnt(0)
	v_mfma_f32_16x16x32_bf16 v[126:129], v[154:157], v[188:191], v[126:129]
	v_mfma_f32_16x16x32_bf16 v[122:125], v[164:167], v[188:191], v[122:125]
	v_mfma_f32_16x16x32_bf16 v[110:113], v[154:157], v[208:211], v[110:113]
	v_mfma_f32_16x16x32_bf16 v[106:109], v[164:167], v[208:211], v[106:109]
	v_mfma_f32_16x16x32_bf16 v[94:97], v[154:157], v[216:219], v[94:97]
	v_mfma_f32_16x16x32_bf16 v[90:93], v[164:167], v[216:219], v[90:93]
	v_mfma_f32_16x16x32_bf16 v[78:81], v[154:157], v[224:227], v[78:81]
	v_mfma_f32_16x16x32_bf16 v[74:77], v[164:167], v[224:227], v[74:77]
	v_mfma_f32_16x16x32_bf16 v[126:129], v[160:163], v[204:207], v[126:129]
	v_mfma_f32_16x16x32_bf16 v[122:125], v[168:171], v[204:207], v[122:125]
	v_mfma_f32_16x16x32_bf16 v[110:113], v[160:163], v[212:215], v[110:113]
	v_mfma_f32_16x16x32_bf16 v[106:109], v[168:171], v[212:215], v[106:109]
	v_mfma_f32_16x16x32_bf16 v[94:97], v[160:163], v[220:223], v[94:97]
	v_mfma_f32_16x16x32_bf16 v[90:93], v[168:171], v[220:223], v[90:93]
	v_mfma_f32_16x16x32_bf16 v[78:81], v[160:163], v[228:231], v[78:81]
	v_mfma_f32_16x16x32_bf16 v[74:77], v[168:171], v[228:231], v[74:77]
	s_setprio 0
	s_setprio 1
	v_mfma_f32_16x16x32_bf16 v[118:121], v[172:175], v[188:191], v[118:121]
	v_mfma_f32_16x16x32_bf16 v[114:117], v[180:183], v[188:191], v[114:117]
	v_mfma_f32_16x16x32_bf16 v[102:105], v[172:175], v[208:211], v[102:105]
	v_mfma_f32_16x16x32_bf16 v[98:101], v[180:183], v[208:211], v[98:101]
	v_mfma_f32_16x16x32_bf16 v[86:89], v[172:175], v[216:219], v[86:89]
	v_mfma_f32_16x16x32_bf16 v[82:85], v[180:183], v[216:219], v[82:85]
	v_mfma_f32_16x16x32_bf16 v[70:73], v[172:175], v[224:227], v[70:73]
	v_mfma_f32_16x16x32_bf16 v[66:69], v[180:183], v[224:227], v[66:69]
	v_mfma_f32_16x16x32_bf16 v[118:121], v[176:179], v[204:207], v[118:121]
	v_mfma_f32_16x16x32_bf16 v[114:117], v[184:187], v[204:207], v[114:117]
	v_mfma_f32_16x16x32_bf16 v[102:105], v[176:179], v[212:215], v[102:105]
	v_mfma_f32_16x16x32_bf16 v[98:101], v[184:187], v[212:215], v[98:101]
	v_mfma_f32_16x16x32_bf16 v[86:89], v[176:179], v[220:223], v[86:89]
	v_mfma_f32_16x16x32_bf16 v[82:85], v[184:187], v[220:223], v[82:85]
	v_mfma_f32_16x16x32_bf16 v[70:73], v[176:179], v[228:231], v[70:73]
	v_mfma_f32_16x16x32_bf16 v[66:69], v[184:187], v[228:231], v[66:69]
	s_setprio 0
	s_barrier
	s_add_i32 s4, s12, s30
	v_lshl_add_u64 v[232:233], s[50:51], 0, v[0:1]
	s_mov_b32 m0, s4
	ds_read_b128 v[188:191], v159 offset:16384
	ds_read_b128 v[204:207], v159 offset:17408
	ds_read_b128 v[208:211], v159 offset:18432
	ds_read_b128 v[212:215], v159 offset:19456
	ds_read_b128 v[216:219], v159 offset:20480
	ds_read_b128 v[220:223], v159 offset:21504
	ds_read_b128 v[224:227], v159 offset:22528
	ds_read_b128 v[228:231], v159 offset:23552
	global_load_lds_dwordx4 v[232:233], off
	s_add_i32 m0, s4, 0x2000
	s_add_u32 s4, s50, 0xb0000
	v_lshl_add_u64 v[234:235], s[50:51], 0, v[130:131]
	s_addc_u32 s5, s51, 0
	s_add_i32 s12, s13, s30
	global_load_lds_dwordx4 v[234:235], off
	v_lshl_add_u64 v[236:237], s[4:5], 0, v[0:1]
	s_mov_b32 m0, s12
	v_lshl_add_u64 v[238:239], s[78:79], 0, v[132:133]
	global_load_lds_dwordx4 v[236:237], off
	s_add_i32 m0, s12, 0x2000
	s_nop 0
	global_load_lds_dwordx4 v130, s[4:5]
	v_lshl_add_u64 v[236:237], s[78:79], 0, v[134:135]
	s_mov_b32 m0, s31
	s_nop 0
	global_load_lds_dwordx4 v[236:237], off
	s_mov_b32 m0, s66
	s_nop 0
	global_load_lds_dwordx4 v[238:239], off
	s_waitcnt vmcnt(8)
	s_waitcnt lgkmcnt(0)
	s_barrier
	s_setprio 1
	s_waitcnt lgkmcnt(0)
	v_mfma_f32_16x16x32_bf16 v[62:65], v[154:157], v[188:191], v[62:65]
	v_mfma_f32_16x16x32_bf16 v[58:61], v[164:167], v[188:191], v[58:61]
	v_mfma_f32_16x16x32_bf16 v[46:49], v[154:157], v[208:211], v[46:49]
	v_mfma_f32_16x16x32_bf16 v[42:45], v[164:167], v[208:211], v[42:45]
	v_mfma_f32_16x16x32_bf16 v[30:33], v[154:157], v[216:219], v[30:33]
	v_mfma_f32_16x16x32_bf16 v[26:29], v[164:167], v[216:219], v[26:29]
	v_mfma_f32_16x16x32_bf16 v[14:17], v[154:157], v[224:227], v[14:17]
	v_mfma_f32_16x16x32_bf16 v[10:13], v[164:167], v[224:227], v[10:13]
	v_mfma_f32_16x16x32_bf16 v[62:65], v[160:163], v[204:207], v[62:65]
	v_mfma_f32_16x16x32_bf16 v[58:61], v[168:171], v[204:207], v[58:61]
	v_mfma_f32_16x16x32_bf16 v[46:49], v[160:163], v[212:215], v[46:49]
	v_mfma_f32_16x16x32_bf16 v[42:45], v[168:171], v[212:215], v[42:45]
	v_mfma_f32_16x16x32_bf16 v[30:33], v[160:163], v[220:223], v[30:33]
	v_mfma_f32_16x16x32_bf16 v[26:29], v[168:171], v[220:223], v[26:29]
	v_mfma_f32_16x16x32_bf16 v[14:17], v[160:163], v[228:231], v[14:17]
	v_mfma_f32_16x16x32_bf16 v[10:13], v[168:171], v[228:231], v[10:13]
	s_setprio 0
	s_setprio 1
	v_mfma_f32_16x16x32_bf16 v[54:57], v[172:175], v[188:191], v[54:57]
	v_mfma_f32_16x16x32_bf16 v[50:53], v[180:183], v[188:191], v[50:53]
	v_mfma_f32_16x16x32_bf16 v[38:41], v[172:175], v[208:211], v[38:41]
	v_mfma_f32_16x16x32_bf16 v[34:37], v[180:183], v[208:211], v[34:37]
	v_mfma_f32_16x16x32_bf16 v[22:25], v[172:175], v[216:219], v[22:25]
	v_mfma_f32_16x16x32_bf16 v[18:21], v[180:183], v[216:219], v[18:21]
	v_mfma_f32_16x16x32_bf16 v[6:9], v[172:175], v[224:227], v[6:9]
	v_mfma_f32_16x16x32_bf16 v[2:5], v[180:183], v[224:227], v[2:5]
	v_mfma_f32_16x16x32_bf16 v[54:57], v[176:179], v[204:207], v[54:57]
	v_mfma_f32_16x16x32_bf16 v[50:53], v[184:187], v[204:207], v[50:53]
	v_mfma_f32_16x16x32_bf16 v[38:41], v[176:179], v[212:215], v[38:41]
	v_mfma_f32_16x16x32_bf16 v[34:37], v[184:187], v[212:215], v[34:37]
	v_mfma_f32_16x16x32_bf16 v[22:25], v[176:179], v[220:223], v[22:25]
	v_mfma_f32_16x16x32_bf16 v[18:21], v[184:187], v[220:223], v[18:21]
	v_mfma_f32_16x16x32_bf16 v[6:9], v[176:179], v[228:231], v[6:9]
	v_mfma_f32_16x16x32_bf16 v[2:5], v[184:187], v[228:231], v[2:5]
	s_setprio 0
	s_barrier
	s_add_i32 s12, 0, 0x18000
	s_add_i32 s13, 0, 0x1c000
	v_add_u32_e32 v168, s12, v158
	v_add_u32_e32 v184, s13, v158
	ds_read_b128 v[154:157], v168
	ds_read_b128 v[160:163], v168 offset:1024
	ds_read_b128 v[164:167], v168 offset:2048
	ds_read_b128 v[168:171], v168 offset:3072
	ds_read_b128 v[172:175], v184
	ds_read_b128 v[176:179], v184 offset:1024
	ds_read_b128 v[180:183], v184 offset:2048
	ds_read_b128 v[184:187], v184 offset:3072
	s_add_u32 s4, s78, 0xb0000
	s_addc_u32 s5, s79, 0
	s_mov_b32 m0, s67
	ds_read_b128 v[188:191], v159 offset:32768
	ds_read_b128 v[204:207], v159 offset:33792
	ds_read_b128 v[208:211], v159 offset:34816
	ds_read_b128 v[212:215], v159 offset:35840
	ds_read_b128 v[216:219], v159 offset:36864
	ds_read_b128 v[220:223], v159 offset:37888
	ds_read_b128 v[224:227], v159 offset:38912
	ds_read_b128 v[228:231], v159 offset:39936
	global_load_lds_dwordx4 v134, s[4:5]
	v_lshl_add_u64 v[240:241], s[4:5], 0, v[132:133]
	s_mov_b32 m0, s80
	s_nop 0
	global_load_lds_dwordx4 v[240:241], off
	s_waitcnt vmcnt(8)
	s_waitcnt lgkmcnt(0)
	s_barrier
	s_setprio 1
	s_waitcnt lgkmcnt(0)
	v_mfma_f32_16x16x32_bf16 v[126:129], v[154:157], v[188:191], v[126:129]
	v_mfma_f32_16x16x32_bf16 v[122:125], v[164:167], v[188:191], v[122:125]
	v_mfma_f32_16x16x32_bf16 v[110:113], v[154:157], v[208:211], v[110:113]
	v_mfma_f32_16x16x32_bf16 v[106:109], v[164:167], v[208:211], v[106:109]
	v_mfma_f32_16x16x32_bf16 v[94:97], v[154:157], v[216:219], v[94:97]
	v_mfma_f32_16x16x32_bf16 v[90:93], v[164:167], v[216:219], v[90:93]
	v_mfma_f32_16x16x32_bf16 v[78:81], v[154:157], v[224:227], v[78:81]
	v_mfma_f32_16x16x32_bf16 v[74:77], v[164:167], v[224:227], v[74:77]
	v_mfma_f32_16x16x32_bf16 v[126:129], v[160:163], v[204:207], v[126:129]
	v_mfma_f32_16x16x32_bf16 v[122:125], v[168:171], v[204:207], v[122:125]
	v_mfma_f32_16x16x32_bf16 v[110:113], v[160:163], v[212:215], v[110:113]
	v_mfma_f32_16x16x32_bf16 v[106:109], v[168:171], v[212:215], v[106:109]
	v_mfma_f32_16x16x32_bf16 v[94:97], v[160:163], v[220:223], v[94:97]
	v_mfma_f32_16x16x32_bf16 v[90:93], v[168:171], v[220:223], v[90:93]
	v_mfma_f32_16x16x32_bf16 v[78:81], v[160:163], v[228:231], v[78:81]
	v_mfma_f32_16x16x32_bf16 v[74:77], v[168:171], v[228:231], v[74:77]
	s_setprio 0
	s_setprio 1
	v_mfma_f32_16x16x32_bf16 v[118:121], v[172:175], v[188:191], v[118:121]
	v_mfma_f32_16x16x32_bf16 v[114:117], v[180:183], v[188:191], v[114:117]
	v_mfma_f32_16x16x32_bf16 v[102:105], v[172:175], v[208:211], v[102:105]
	v_mfma_f32_16x16x32_bf16 v[98:101], v[180:183], v[208:211], v[98:101]
	v_mfma_f32_16x16x32_bf16 v[86:89], v[172:175], v[216:219], v[86:89]
	v_mfma_f32_16x16x32_bf16 v[82:85], v[180:183], v[216:219], v[82:85]
	v_mfma_f32_16x16x32_bf16 v[70:73], v[172:175], v[224:227], v[70:73]
	v_mfma_f32_16x16x32_bf16 v[66:69], v[180:183], v[224:227], v[66:69]
	v_mfma_f32_16x16x32_bf16 v[118:121], v[176:179], v[204:207], v[118:121]
	v_mfma_f32_16x16x32_bf16 v[114:117], v[184:187], v[204:207], v[114:117]
	v_mfma_f32_16x16x32_bf16 v[102:105], v[176:179], v[212:215], v[102:105]
	v_mfma_f32_16x16x32_bf16 v[98:101], v[184:187], v[212:215], v[98:101]
	v_mfma_f32_16x16x32_bf16 v[86:89], v[176:179], v[220:223], v[86:89]
	v_mfma_f32_16x16x32_bf16 v[82:85], v[184:187], v[220:223], v[82:85]
	v_mfma_f32_16x16x32_bf16 v[70:73], v[176:179], v[228:231], v[70:73]
	v_mfma_f32_16x16x32_bf16 v[66:69], v[184:187], v[228:231], v[66:69]
	s_setprio 0
	s_barrier
	s_add_i32 s4, s12, s30
	v_lshl_add_u64 v[232:233], v[232:233], 0, s[14:15]
	s_mov_b32 m0, s4
	ds_read_b128 v[188:191], v159 offset:49152
	ds_read_b128 v[204:207], v159 offset:50176
	ds_read_b128 v[208:211], v159 offset:51200
	ds_read_b128 v[212:215], v159 offset:52224
	ds_read_b128 v[216:219], v159 offset:53248
	ds_read_b128 v[220:223], v159 offset:54272
	ds_read_b128 v[224:227], v159 offset:55296
	ds_read_b128 v[228:231], v159 offset:56320
	global_load_lds_dwordx4 v[232:233], off
	s_add_i32 m0, s4, 0x2000
	s_add_u32 s4, s50, 0xb0080
	v_lshl_add_u64 v[232:233], v[234:235], 0, s[14:15]
	s_addc_u32 s5, s51, 0
	s_add_i32 s12, s13, s30
	global_load_lds_dwordx4 v[232:233], off
	v_lshl_add_u64 v[232:233], s[4:5], 0, v[0:1]
	s_mov_b32 m0, s12
	s_nop 0
	global_load_lds_dwordx4 v[232:233], off
	s_add_i32 m0, s12, 0x2000
	s_nop 0
	global_load_lds_dwordx4 v130, s[4:5]
	v_lshl_add_u64 v[232:233], v[236:237], 0, s[14:15]
	s_mov_b32 m0, s81
	s_nop 0
	global_load_lds_dwordx4 v[232:233], off
	v_lshl_add_u64 v[232:233], v[238:239], 0, s[14:15]
	s_mov_b32 m0, s82
	s_nop 0
	global_load_lds_dwordx4 v[232:233], off
	s_waitcnt vmcnt(8)
	s_waitcnt lgkmcnt(0)
	s_barrier
	s_setprio 1
	s_waitcnt lgkmcnt(0)
	v_mfma_f32_16x16x32_bf16 v[62:65], v[154:157], v[188:191], v[62:65]
	v_mfma_f32_16x16x32_bf16 v[58:61], v[164:167], v[188:191], v[58:61]
	v_mfma_f32_16x16x32_bf16 v[46:49], v[154:157], v[208:211], v[46:49]
	v_mfma_f32_16x16x32_bf16 v[42:45], v[164:167], v[208:211], v[42:45]
	v_mfma_f32_16x16x32_bf16 v[30:33], v[154:157], v[216:219], v[30:33]
	v_mfma_f32_16x16x32_bf16 v[26:29], v[164:167], v[216:219], v[26:29]
	v_mfma_f32_16x16x32_bf16 v[14:17], v[154:157], v[224:227], v[14:17]
	v_mfma_f32_16x16x32_bf16 v[10:13], v[164:167], v[224:227], v[10:13]
	v_mfma_f32_16x16x32_bf16 v[62:65], v[160:163], v[204:207], v[62:65]
	v_mfma_f32_16x16x32_bf16 v[58:61], v[168:171], v[204:207], v[58:61]
	v_mfma_f32_16x16x32_bf16 v[46:49], v[160:163], v[212:215], v[46:49]
	v_mfma_f32_16x16x32_bf16 v[42:45], v[168:171], v[212:215], v[42:45]
	v_mfma_f32_16x16x32_bf16 v[30:33], v[160:163], v[220:223], v[30:33]
	v_mfma_f32_16x16x32_bf16 v[26:29], v[168:171], v[220:223], v[26:29]
	v_mfma_f32_16x16x32_bf16 v[14:17], v[160:163], v[228:231], v[14:17]
	v_mfma_f32_16x16x32_bf16 v[10:13], v[168:171], v[228:231], v[10:13]
	s_setprio 0
	s_setprio 1
	v_mfma_f32_16x16x32_bf16 v[54:57], v[172:175], v[188:191], v[54:57]
	v_mfma_f32_16x16x32_bf16 v[50:53], v[180:183], v[188:191], v[50:53]
	v_mfma_f32_16x16x32_bf16 v[38:41], v[172:175], v[208:211], v[38:41]
	v_mfma_f32_16x16x32_bf16 v[34:37], v[180:183], v[208:211], v[34:37]
	v_mfma_f32_16x16x32_bf16 v[22:25], v[172:175], v[216:219], v[22:25]
	v_mfma_f32_16x16x32_bf16 v[18:21], v[180:183], v[216:219], v[18:21]
	v_mfma_f32_16x16x32_bf16 v[6:9], v[172:175], v[224:227], v[6:9]
	v_mfma_f32_16x16x32_bf16 v[2:5], v[180:183], v[224:227], v[2:5]
	v_mfma_f32_16x16x32_bf16 v[54:57], v[176:179], v[204:207], v[54:57]
	v_mfma_f32_16x16x32_bf16 v[50:53], v[184:187], v[204:207], v[50:53]
	v_mfma_f32_16x16x32_bf16 v[38:41], v[176:179], v[212:215], v[38:41]
	v_mfma_f32_16x16x32_bf16 v[34:37], v[184:187], v[212:215], v[34:37]
	v_mfma_f32_16x16x32_bf16 v[22:25], v[176:179], v[220:223], v[22:25]
	v_mfma_f32_16x16x32_bf16 v[18:21], v[184:187], v[220:223], v[18:21]
	v_mfma_f32_16x16x32_bf16 v[6:9], v[176:179], v[228:231], v[6:9]
	v_mfma_f32_16x16x32_bf16 v[2:5], v[184:187], v[228:231], v[2:5]
	s_setprio 0
	s_barrier
	s_add_i32 s77, s77, 2
	s_add_u32 s86, s86, 0x100
	s_addc_u32 s87, s87, 0
	s_cmp_gt_u32 s77, 41
	s_mov_b64 s[4:5], s[48:49]
	s_cbranch_scc0 .LBB0_1378
	s_and_b64 vcc, exec, s[42:43]
	s_cbranch_vccz .LBB0_1381
	s_barrier
